# P0 initial rmsnorm: gain quads preloaded once before the row loop (no per-row reload behind stores)
# speedup vs baseline: 1.0081x; 1.0039x over previous
; __device__ __forceinline__ unsigned pk2(float lo, float hi) { f32x2 v = {lo, hi}; bf16x2_t b = __builtin_convertvector(v, bf16x2_t); return __builtin_bit_cast(unsigned, b); }
; __device__ __forceinline__ void rms_row_to_bf16(const float* xrow, const float* gain, bf16* orow, int lane) {
;     f32x4 v[4]; float s = 0.f;
; #pragma unroll
;     for (int j = 0; j < 4; ++j) { v[j] = xrow ? ((const f32x4*)xrow)[lane + 64 * j] : (f32x4){0.f, 0.f, 0.f, 0.f}; s += (v[j].x * v[j].x + v[j].y * v[j].y) + (v[j].z * v[j].z + v[j].w * v[j].w); }
;     const float rstd = 1.f / sqrtf(wave_sum(s) * (1.f / DM) + EPS);
; #pragma unroll
;     for (int j = 0; j < 4; ++j) { const f32x4 g = ((const f32x4*)gain)[lane + 64 * j];
;         u32x2 o; o.x = pk2(v[j].x * rstd * g.x, v[j].y * rstd * g.y); o.y = pk2(v[j].z * rstd * g.z, v[j].w * rstd * g.w);
;         ((u32x2*)orow)[lane + 64 * j] = o; }
; }
; __device__ __forceinline__ void p0_prologue(const Args& a, LAS unsigned char* lds, int vcu, int G, int tid, int lane, int wave) {
;     ...
;     for (int m0 = gw; m0 < MT; m0 += 2 * NGW)
; #pragma unroll
;     for (int qq = 0; qq < 2; ++qq) { const int m = m0 + qq * NGW; if (m >= MT) break;
;         rms_row_to_bf16(xrow_ptr(a, m, z), (const float*)a.in[I_F1PRE + z], (bf16*)(ws + WS_XN) + (size_t)m * DM, lane);
.LBB0_36:
	s_or_b64 exec, exec, s[12:13]
	s_cmpk_gt_i32 s6, 0x40ff
	s_cbranch_scc1 .LBB0_83
	s_load_dwordx2 s[2:3], s[4:5], 0x48
	v_and_b32_e32 v0, 63, v14
	v_mov_b32_e32 v3, 0
	v_lshlrev_b32_e32 v2, 3, v0
	s_waitcnt lgkmcnt(0)
	v_lshl_add_u64 v[4:5], s[8:9], 0, v[2:3]
	v_lshlrev_b32_e32 v2, 4, v0
	s_mov_b64 s[8:9], 0x25100000
	v_lshl_add_u64 v[18:19], s[2:3], 0, v[2:3]
	global_load_dwordx4 v[40:43], v[18:19], off
	global_load_dwordx4 v[44:47], v[18:19], off offset:1024
	global_load_dwordx4 v[48:51], v[18:19], off offset:2048
	global_load_dwordx4 v[52:55], v[18:19], off offset:3072
	s_mov_b64 s[2:3], 0x4000000
	v_lshl_add_u64 v[16:17], v[4:5], 0, s[8:9]
	v_lshl_add_u64 v[20:21], v[4:5], 0, s[2:3]
	s_mov_b32 s9, 0
	v_mov_b32_e32 v22, 0x358637bd
	s_mov_b32 s16, 0xf800000
	v_mov_b32_e32 v23, 0x260
	v_lshlrev_b32_e32 v24, 4, v0
	s_waitcnt vmcnt(0)
	s_branch .LBB0_42

; __device__ __forceinline__ unsigned pk2(float lo, float hi) { f32x2 v = {lo, hi}; bf16x2_t b = __builtin_convertvector(v, bf16x2_t); return __builtin_bit_cast(unsigned, b); }
; __device__ __forceinline__ void rms_row_to_bf16(const float* xrow, const float* gain, bf16* orow, int lane) {
;     f32x4 v[4]; float s = 0.f;
; #pragma unroll
;     for (int j = 0; j < 4; ++j) { v[j] = xrow ? ((const f32x4*)xrow)[lane + 64 * j] : (f32x4){0.f, 0.f, 0.f, 0.f}; s += (v[j].x * v[j].x + v[j].y * v[j].y) + (v[j].z * v[j].z + v[j].w * v[j].w); }
;     const float rstd = 1.f / sqrtf(wave_sum(s) * (1.f / DM) + EPS);
; #pragma unroll
;     for (int j = 0; j < 4; ++j) { const f32x4 g = ((const f32x4*)gain)[lane + 64 * j];
;         u32x2 o; o.x = pk2(v[j].x * rstd * g.x, v[j].y * rstd * g.y); o.y = pk2(v[j].z * rstd * g.z, v[j].w * rstd * g.w);
;         ((u32x2*)orow)[lane + 64 * j] = o; }
; }
.LBB0_55:
	v_mov_b64_e32 v[26:27], v[40:41]
	v_mov_b64_e32 v[28:29], v[42:43]
	s_waitcnt vmcnt(0)
	v_mul_f32_e32 v25, v9, v9
	v_mul_f32_e32 v30, v11, v11
	v_mul_f32_e32 v31, v1, v1
	v_mul_f32_e32 v32, v3, v3
	v_mul_f32_e32 v33, v13, v13
	v_mul_f32_e32 v34, v15, v15
	v_fmac_f32_e32 v25, v8, v8
	v_fmac_f32_e32 v30, v10, v10
	v_fmac_f32_e32 v31, v0, v0
	v_fmac_f32_e32 v32, v2, v2
	v_mul_f32_e32 v35, v5, v5
	v_mul_f32_e32 v36, v7, v7
	v_fmac_f32_e32 v33, v12, v12
	v_fmac_f32_e32 v34, v14, v14
	v_add_f32_e32 v25, v25, v30
	v_add_f32_e32 v30, v31, v32
	v_fmac_f32_e32 v35, v4, v4
	v_fmac_f32_e32 v36, v6, v6
	v_add_f32_e32 v31, v33, v34
	v_add_f32_e32 v25, v25, v30
	v_add_f32_e32 v32, v35, v36
	v_add_f32_e32 v25, v25, v31
	v_add_f32_e32 v25, v25, v32
	s_ashr_i32 s7, s6, 31
	s_lshl_b64 s[12:13], s[6:7], 11
	v_add_f32_dpp v25, v25, v25 quad_perm:[1,0,3,2] row_mask:0xf bank_mask:0xf bound_ctrl:1
	s_nop 1
	v_add_f32_dpp v25, v25, v25 quad_perm:[2,3,0,1] row_mask:0xf bank_mask:0xf bound_ctrl:1
	s_nop 1
	v_add_f32_dpp v25, v25, v25 row_half_mirror row_mask:0xf bank_mask:0xf bound_ctrl:1
	s_nop 1
	v_add_f32_dpp v25, v25, v25 row_mirror row_mask:0xf bank_mask:0xf bound_ctrl:1
	v_mov_b32_e32 v30, v25
	s_nop 1
	v_permlane16_swap_b32_e32 v25, v30
	v_add_f32_e32 v25, v25, v30
	v_mov_b32_e32 v30, v25
	s_nop 1
	v_permlane32_swap_b32_e32 v25, v30
	v_add_f32_e32 v25, v25, v30
	v_fmamk_f32 v25, v25, 0x3a800000, v22
	v_mul_f32_e32 v30, 0x4f800000, v25
	v_cmp_gt_f32_e32 vcc, s16, v25
	s_nop 1
	v_cndmask_b32_e32 v25, v25, v30, vcc
	v_sqrt_f32_e32 v30, v25
	s_nop 0
	v_add_u32_e32 v31, -1, v30
	v_add_u32_e32 v32, 1, v30
	v_fma_f32 v33, -v31, v30, v25
	v_fma_f32 v34, -v32, v30, v25
	v_cmp_ge_f32_e64 s[2:3], 0, v33
	s_nop 1
	v_cndmask_b32_e64 v30, v30, v31, s[2:3]
	v_cmp_lt_f32_e64 s[2:3], 0, v34
	s_nop 1
	v_cndmask_b32_e64 v30, v30, v32, s[2:3]
	v_mul_f32_e32 v31, 0x37800000, v30
	v_cndmask_b32_e32 v30, v30, v31, vcc
	v_cmp_class_f32_e32 vcc, v25, v23
	s_nop 1
	v_cndmask_b32_e32 v25, v30, v25, vcc
	v_div_scale_f32 v32, s[2:3], v25, v25, 1.0
	v_rcp_f32_e32 v33, v32
	v_div_scale_f32 v34, vcc, 1.0, v25, 1.0
	v_lshl_add_u64 v[30:31], v[20:21], 0, s[12:13]
	v_fma_f32 v35, -v32, v33, 1.0
	v_fmac_f32_e32 v33, v35, v33
	v_mul_f32_e32 v35, v34, v33
	v_fma_f32 v36, -v32, v35, v34
	v_fmac_f32_e32 v35, v36, v33
	v_fma_f32 v32, -v32, v35, v34
	v_div_fmas_f32 v32, v32, v33, v35
	v_div_fixup_f32 v32, v32, v25, 1.0
	v_pk_mul_f32 v[8:9], v[8:9], v[32:33] op_sel_hi:[1,0]
	v_pk_mul_f32 v[10:11], v[10:11], v[32:33] op_sel_hi:[1,0]
	v_pk_mul_f32 v[8:9], v[26:27], v[8:9]
	v_pk_mul_f32 v[10:11], v[28:29], v[10:11]
	v_cvt_pk_bf16_f32 v8, v8, v9
	v_cvt_pk_bf16_f32 v9, v10, v11
	global_store_dwordx2 v[30:31], v[8:9], off
	s_nop 0
	v_mov_b64_e32 v[8:9], v[44:45]
	v_mov_b64_e32 v[10:11], v[46:47]
	v_pk_mul_f32 v[0:1], v[0:1], v[32:33] op_sel_hi:[1,0]
	v_pk_mul_f32 v[2:3], v[2:3], v[32:33] op_sel_hi:[1,0]
	v_pk_mul_f32 v[4:5], v[4:5], v[32:33] op_sel_hi:[1,0]
	v_pk_mul_f32 v[6:7], v[6:7], v[32:33] op_sel_hi:[1,0]
	s_mov_b64 s[12:13], -1
	s_and_b64 vcc, exec, s[10:11]
	v_pk_mul_f32 v[0:1], v[8:9], v[0:1]
	v_pk_mul_f32 v[2:3], v[10:11], v[2:3]
	v_cvt_pk_bf16_f32 v0, v0, v1
	v_cvt_pk_bf16_f32 v1, v2, v3
	global_store_dwordx2 v[30:31], v[0:1], off offset:512
	s_nop 0
	v_mov_b64_e32 v[0:1], v[48:49]
	v_mov_b64_e32 v[2:3], v[50:51]
	v_pk_mul_f32 v[8:9], v[12:13], v[32:33] op_sel_hi:[1,0]
	v_pk_mul_f32 v[10:11], v[14:15], v[32:33] op_sel_hi:[1,0]
	v_pk_mul_f32 v[0:1], v[0:1], v[8:9]
	v_pk_mul_f32 v[2:3], v[2:3], v[10:11]
	v_cvt_pk_bf16_f32 v0, v0, v1
	v_cvt_pk_bf16_f32 v1, v2, v3
	global_store_dwordx2 v[30:31], v[0:1], off offset:1024
	s_nop 0
	v_mov_b64_e32 v[0:1], v[52:53]
	v_mov_b64_e32 v[2:3], v[54:55]
	v_pk_mul_f32 v[0:1], v[4:5], v[0:1]
	v_pk_mul_f32 v[2:3], v[6:7], v[2:3]
	v_cvt_pk_bf16_f32 v0, v0, v1
	v_cvt_pk_bf16_f32 v1, v2, v3
	global_store_dwordx2 v[30:31], v[0:1], off offset:1536
	s_cbranch_vccz .LBB0_58
	s_mov_b64 s[12:13], 0
	s_cmpk_gt_u32 s6, 0x407f
	s_mov_b64 s[2:3], 0
	s_cbranch_scc1 .LBB0_58
	s_load_dwordx2 s[2:3], s[4:5], 0x18
	s_add_i32 s8, s6, 0xffffc000
	s_lshl_b64 s[10:11], s[8:9], 10
	s_waitcnt lgkmcnt(0)
	s_add_u32 s2, s2, s10
	s_addc_u32 s3, s3, s11

; __device__ __forceinline__ unsigned pk2(float lo, float hi) { f32x2 v = {lo, hi}; bf16x2_t b = __builtin_convertvector(v, bf16x2_t); return __builtin_bit_cast(unsigned, b); }
; __device__ __forceinline__ void rms_row_to_bf16(const float* xrow, const float* gain, bf16* orow, int lane) {
;     f32x4 v[4]; float s = 0.f;
; #pragma unroll
;     for (int j = 0; j < 4; ++j) { v[j] = xrow ? ((const f32x4*)xrow)[lane + 64 * j] : (f32x4){0.f, 0.f, 0.f, 0.f}; s += (v[j].x * v[j].x + v[j].y * v[j].y) + (v[j].z * v[j].z + v[j].w * v[j].w); }
;     const float rstd = 1.f / sqrtf(wave_sum(s) * (1.f / DM) + EPS);
; #pragma unroll
;     for (int j = 0; j < 4; ++j) { const f32x4 g = ((const f32x4*)gain)[lane + 64 * j];
;         u32x2 o; o.x = pk2(v[j].x * rstd * g.x, v[j].y * rstd * g.y); o.y = pk2(v[j].z * rstd * g.z, v[j].w * rstd * g.w);
;         ((u32x2*)orow)[lane + 64 * j] = o; }
; }
.LBB0_77:
	s_load_dwordx2 s[12:13], s[4:5], 0x48
	s_waitcnt vmcnt(0)
	v_mul_f32_e32 v25, v9, v9
	v_mul_f32_e32 v30, v11, v11
	v_mul_f32_e32 v31, v1, v1
	v_mul_f32_e32 v32, v3, v3
	s_waitcnt lgkmcnt(0)
	v_mov_b64_e32 v[26:27], v[40:41]
	v_mov_b64_e32 v[28:29], v[42:43]
	v_mul_f32_e32 v33, v13, v13
	v_mul_f32_e32 v34, v15, v15
	v_fmac_f32_e32 v25, v8, v8
	v_fmac_f32_e32 v30, v10, v10
	v_fmac_f32_e32 v31, v0, v0
	v_fmac_f32_e32 v32, v2, v2
	v_mul_f32_e32 v35, v5, v5
	v_mul_f32_e32 v36, v7, v7
	v_fmac_f32_e32 v33, v12, v12
	v_fmac_f32_e32 v34, v14, v14
	v_add_f32_e32 v25, v25, v30
	v_add_f32_e32 v30, v31, v32
	v_fmac_f32_e32 v35, v4, v4
	v_fmac_f32_e32 v36, v6, v6
	v_add_f32_e32 v31, v33, v34
	v_add_f32_e32 v25, v25, v30
	v_add_f32_e32 v32, v35, v36
	v_add_f32_e32 v25, v25, v31
	v_add_f32_e32 v25, v25, v32
	s_ashr_i32 s7, s6, 31
	s_lshl_b64 s[14:15], s[6:7], 11
	v_add_f32_dpp v25, v25, v25 quad_perm:[1,0,3,2] row_mask:0xf bank_mask:0xf bound_ctrl:1
	s_nop 1
	v_add_f32_dpp v25, v25, v25 quad_perm:[2,3,0,1] row_mask:0xf bank_mask:0xf bound_ctrl:1
	s_nop 1
	v_add_f32_dpp v25, v25, v25 row_half_mirror row_mask:0xf bank_mask:0xf bound_ctrl:1
	s_nop 1
	v_add_f32_dpp v25, v25, v25 row_mirror row_mask:0xf bank_mask:0xf bound_ctrl:1
	v_mov_b32_e32 v30, v25
	s_nop 1
	v_permlane16_swap_b32_e32 v25, v30
	v_add_f32_e32 v25, v25, v30
	v_mov_b32_e32 v30, v25
	s_nop 1
	v_permlane32_swap_b32_e32 v25, v30
	v_add_f32_e32 v25, v25, v30
	v_fmamk_f32 v25, v25, 0x3a800000, v22
	v_mul_f32_e32 v30, 0x4f800000, v25
	v_cmp_gt_f32_e32 vcc, s16, v25
	s_nop 1
	v_cndmask_b32_e32 v25, v25, v30, vcc
	v_sqrt_f32_e32 v30, v25
	s_nop 0
	v_add_u32_e32 v31, -1, v30
	v_add_u32_e32 v32, 1, v30
	v_fma_f32 v33, -v31, v30, v25
	v_fma_f32 v34, -v32, v30, v25
	v_cmp_ge_f32_e64 s[2:3], 0, v33
	s_nop 1
	v_cndmask_b32_e64 v30, v30, v31, s[2:3]
	v_cmp_lt_f32_e64 s[2:3], 0, v34
	s_nop 1
	v_cndmask_b32_e64 v30, v30, v32, s[2:3]
	v_mul_f32_e32 v31, 0x37800000, v30
	v_cndmask_b32_e32 v30, v30, v31, vcc
	v_cmp_class_f32_e32 vcc, v25, v23
	s_nop 1
	v_cndmask_b32_e32 v25, v30, v25, vcc
	v_div_scale_f32 v32, s[2:3], v25, v25, 1.0
	v_rcp_f32_e32 v33, v32
	v_div_scale_f32 v34, vcc, 1.0, v25, 1.0
	v_lshl_add_u64 v[30:31], v[20:21], 0, s[14:15]
	v_fma_f32 v35, -v32, v33, 1.0
	v_fmac_f32_e32 v33, v35, v33
	v_mul_f32_e32 v35, v34, v33
	v_fma_f32 v36, -v32, v35, v34
	v_fmac_f32_e32 v35, v36, v33
	v_fma_f32 v32, -v32, v35, v34
	v_div_fmas_f32 v32, v32, v33, v35
	v_div_fixup_f32 v32, v32, v25, 1.0
	v_pk_mul_f32 v[8:9], v[8:9], v[32:33] op_sel_hi:[1,0]
	v_pk_mul_f32 v[10:11], v[10:11], v[32:33] op_sel_hi:[1,0]
	v_pk_mul_f32 v[8:9], v[26:27], v[8:9]
	v_pk_mul_f32 v[10:11], v[28:29], v[10:11]
	v_cvt_pk_bf16_f32 v8, v8, v9
	v_cvt_pk_bf16_f32 v9, v10, v11
	global_store_dwordx2 v[30:31], v[8:9], off
	s_nop 0
	v_mov_b64_e32 v[8:9], v[44:45]
	v_mov_b64_e32 v[10:11], v[46:47]
	v_pk_mul_f32 v[0:1], v[0:1], v[32:33] op_sel_hi:[1,0]
	v_pk_mul_f32 v[2:3], v[2:3], v[32:33] op_sel_hi:[1,0]
	v_pk_mul_f32 v[4:5], v[4:5], v[32:33] op_sel_hi:[1,0]
	v_pk_mul_f32 v[6:7], v[6:7], v[32:33] op_sel_hi:[1,0]
	s_andn2_b64 vcc, exec, s[10:11]
	s_mov_b64 s[10:11], -1
	v_pk_mul_f32 v[0:1], v[8:9], v[0:1]
	v_pk_mul_f32 v[2:3], v[10:11], v[2:3]
	v_cvt_pk_bf16_f32 v0, v0, v1
	v_cvt_pk_bf16_f32 v1, v2, v3
	global_store_dwordx2 v[30:31], v[0:1], off offset:512
	s_nop 0
	v_mov_b64_e32 v[0:1], v[48:49]
	v_mov_b64_e32 v[2:3], v[50:51]
	v_pk_mul_f32 v[8:9], v[12:13], v[32:33] op_sel_hi:[1,0]
	v_pk_mul_f32 v[10:11], v[14:15], v[32:33] op_sel_hi:[1,0]
	v_pk_mul_f32 v[0:1], v[0:1], v[8:9]
	v_pk_mul_f32 v[2:3], v[2:3], v[10:11]
	v_cvt_pk_bf16_f32 v0, v0, v1
	v_cvt_pk_bf16_f32 v1, v2, v3
	global_store_dwordx2 v[30:31], v[0:1], off offset:1024
	s_nop 0
	v_mov_b64_e32 v[0:1], v[52:53]
	v_mov_b64_e32 v[2:3], v[54:55]
	v_pk_mul_f32 v[0:1], v[4:5], v[0:1]
	v_pk_mul_f32 v[2:3], v[6:7], v[2:3]
	v_cvt_pk_bf16_f32 v0, v0, v1
	v_cvt_pk_bf16_f32 v1, v2, v3
	global_store_dwordx2 v[30:31], v[0:1], off offset:1536
	s_cbranch_vccnz .LBB0_80
	s_mov_b64 s[10:11], 0
	s_cmpk_gt_u32 s6, 0x407f
	s_mov_b64 s[2:3], 0
	s_cbranch_scc1 .LBB0_80
	s_load_dwordx2 s[2:3], s[4:5], 0x18
	s_add_i32 s8, s6, 0xffffc000
	s_lshl_b64 s[12:13], s[8:9], 10
	s_waitcnt lgkmcnt(0)
	s_add_u32 s2, s2, s12
	s_addc_u32 s3, s3, s13
